# v83 + gMLP layer: w_in -> spatial gating -> w_out as 4-workgroup row-panel hand-offs (gating items remapped to the owning panel; enabled by a runtime XCC-placement check since those producers use plai
# speedup vs baseline: 1.0083x; 1.0020x over previous
; #define LAS __attribute__((address_space(3)))
; __device__ __forceinline__ unsigned xb_add(unsigned* p, unsigned v) { return __hip_atomic_fetch_add(p, v, __ATOMIC_RELAXED, __HIP_MEMORY_SCOPE_AGENT); }
; __device__ __forceinline__ unsigned xb_xcc_id() { return (unsigned)__builtin_amdgcn_s_getreg((3 << 11) | 20) & 0xFu; }
; __device__ __forceinline__ XcdBarrier xcd_barrier_post(unsigned* bar, volatile LAS unsigned* st, int tid) {
;     XcdBarrier b; b.bar = bar; b.x = xb_xcc_id(); b.st = st;
;     if (tid == 0) (void)xb_add(&bar[XB_XCNT(b.x)], 1u);
;     return b;
; __global__ void __launch_bounds__(NWAVES * 64, 2) fwd_kernel(Args args) {
;     ...
;     const int lo = args.ph_lo, hi = args.ph_hi;
;     int ph = 0;
;     if (tid0 < 2) ((volatile LAS unsigned*)(L + LDS_BARST))[tid0] = 0u;
;     __syncthreads();
;     XcdBarrier xbar = xcd_barrier_post((unsigned*)(A_->ws + WS_BAR), (volatile LAS unsigned*)(L + LDS_BARST), tid0);
_Z10fwd_kernel4Args:
	s_mov_b64 s[94:95], s[0:1]
	s_load_dwordx4 s[80:83], s[0:1], 0xc0
	s_load_dword s17, s[0:1], 0xd0
	s_add_u32 s0, s94, 0xc8
	s_addc_u32 s1, s95, 0
	v_and_b32_e32 v215, 0x3ff, v0
	v_writelane_b32 v254, s0, 0
	s_mov_b32 s84, s2
	v_cmp_gt_u32_e32 vcc, 2, v215
	v_writelane_b32 v254, s1, 1
	s_mov_b32 s98, 0
	v_writelane_b32 v255, s98, 57
	s_mov_b32 s98, 0
	v_writelane_b32 v255, s98, 59
	s_and_saveexec_b64 s[0:1], vcc
	v_lshl_add_u32 v1, v215, 2, 0
	v_add_u32_e32 v1, 0x23fc0, v1
	v_mov_b32_e32 v2, 0
	ds_write_b32 v1, v2
	s_or_b64 exec, exec, s[0:1]
	s_waitcnt lgkmcnt(0)
	s_barrier
	s_load_dwordx2 s[0:1], s[94:95], 0xb8
	s_getreg_b32 s4, hwreg(HW_REG_XCC_ID, 0, 4)
	v_cmp_eq_u32_e32 vcc, 0, v215
	s_waitcnt lgkmcnt(0)
	s_add_u32 s2, s0, 0xe0000
	s_addc_u32 s3, s1, 0
	s_and_b32 s16, s4, 15
	s_and_saveexec_b64 s[4:5], vcc
	s_cbranch_execz .LBB0_5
	s_mov_b64 s[6:7], exec
	v_mbcnt_lo_u32_b32 v1, s6, 0
	v_mbcnt_hi_u32_b32 v1, s7, v1
	v_cmp_eq_u32_e32 vcc, 0, v1
	s_and_b64 s[8:9], exec, vcc
	s_mov_b64 exec, s[8:9]
	s_cbranch_execz .LBB0_5
	s_lshl_b32 s8, s16, 8
	s_bcnt1_i32_b64 s6, s[6:7]
	v_mov_b32_e32 v1, s8
	v_mov_b32_e32 v2, s6
	global_atomic_add v1, v2, s[2:3] offset:1024
	s_and_b32 s100, s84, 7
	s_lshl_b32 s100, s100, 5
	s_add_i32 s100, s100, 0x2c08
	s_lshl_b32 s101, 1, s16
	v_mov_b32_e32 v3, s100
	v_mov_b32_e32 v4, s101
	global_atomic_or v3, v4, s[2:3]

; #define LAS __attribute__((address_space(3)))
; __global__ void __launch_bounds__(NWAVES * 64, 2) fwd_kernel(Args args) {
;     ...
;     const int lo = args.ph_lo, hi = args.ph_hi;
;     int ph = 0;
;     if (tid0 < 2) ((volatile LAS unsigned*)(L + LDS_BARST))[tid0] = 0u;
;     __syncthreads();
;     XcdBarrier xbar = xcd_barrier_post((unsigned*)(A_->ws + WS_BAR), (volatile LAS unsigned*)(L + LDS_BARST), tid0);
.LBB0_154:
	v_mov_b32_e32 v1, 0
	s_add_u32 s100, s0, 0xe2c08
	s_addc_u32 s101, s1, 0
	global_load_dword v2, v1, s[100:101] sc1
	global_load_dword v3, v1, s[100:101] offset:32 sc1
	global_load_dword v4, v1, s[100:101] offset:64 sc1
	global_load_dword v5, v1, s[100:101] offset:96 sc1
	global_load_dword v6, v1, s[100:101] offset:128 sc1
	global_load_dword v7, v1, s[100:101] offset:160 sc1
	global_load_dword v8, v1, s[100:101] offset:192 sc1
	global_load_dword v9, v1, s[100:101] offset:224 sc1
	s_waitcnt vmcnt(0)
	v_bcnt_u32_b32 v2, v2, 0
	v_bcnt_u32_b32 v3, v3, 0
	v_bcnt_u32_b32 v4, v4, 0
	v_bcnt_u32_b32 v5, v5, 0
	v_bcnt_u32_b32 v6, v6, 0
	v_bcnt_u32_b32 v7, v7, 0
	v_bcnt_u32_b32 v8, v8, 0
	v_bcnt_u32_b32 v9, v9, 0
	v_max3_u32 v10, v2, v3, v4
	v_max3_u32 v10, v10, v5, v6
	v_max3_u32 v10, v10, v7, v8
	v_max_u32_e32 v10, v10, v9
	v_min3_u32 v11, v2, v3, v4
	v_min3_u32 v11, v11, v5, v6
	v_min3_u32 v11, v11, v7, v8
	v_min_u32_e32 v11, v11, v9
	s_nop 0
	v_readfirstlane_b32 s100, v10
	v_readfirstlane_b32 s101, v11
	s_cmp_eq_u32 s100, 1
	s_cselect_b32 s100, 1, 0
	s_cmp_eq_u32 s101, 1
	s_cselect_b32 s100, s100, 0
	v_writelane_b32 v255, s100, 57
	s_cmp_lt_i32 s80, 0
	s_cselect_b64 s[6:7], -1, 0
	s_add_u32 s96, s0, 0xe0200
	s_addc_u32 s97, s1, 0
	s_add_u32 s90, s0, 0xe0400
	s_addc_u32 s91, s1, 0
	s_add_u32 s92, s0, 0xe0500
	s_addc_u32 s93, s1, 0
	s_add_u32 s86, s0, 0xe0600
	s_mul_i32 s4, s83, s82
	v_lshrrev_b32_e32 v1, 20, v0
	v_lshrrev_b32_e32 v0, 10, v0
	s_addc_u32 s87, s1, 0
	v_writelane_b32 v254, s6, 3
	v_or_b32_e32 v0, v0, v1
	s_movk_i32 s5, 0x3ff
	s_mul_i32 s83, s4, s17
	s_add_u32 s4, s0, 0xe0700
	v_writelane_b32 v254, s7, 4
	v_and_or_b32 v0, v0, s5, v215
	s_addc_u32 s5, s1, 0
	v_writelane_b32 v254, s4, 5
	s_mov_b32 s9, 0
	v_mov_b32_e32 v213, 0
	v_writelane_b32 v254, s5, 6
	s_add_u32 s4, s0, 0xe0800
	s_addc_u32 s5, s1, 0
	v_writelane_b32 v254, s4, 7
	v_mbcnt_lo_u32_b32 v1, -1, 0
	s_movk_i32 s75, 0x4000
	v_writelane_b32 v254, s5, 8
	s_add_u32 s4, s0, 0xe0900
	s_addc_u32 s5, s1, 0
	v_writelane_b32 v254, s4, 9
	s_movk_i32 s54, 0x6000
	s_mov_b32 s55, 0xc000
	v_writelane_b32 v254, s5, 10
	s_add_u32 s4, s0, 0xe0a00
	s_addc_u32 s5, s1, 0
	v_writelane_b32 v254, s4, 11
	s_mov_b32 s27, 0x800000
	v_mov_b32_e32 v247, 1
	v_writelane_b32 v254, s5, 12
	s_add_u32 s4, s0, 0xe0b00
	s_addc_u32 s5, s1, 0
	v_writelane_b32 v254, s4, 13
	v_mbcnt_hi_u32_b32 v246, -1, v1
	v_mov_b32_e32 v214, 0x358637bd
	v_writelane_b32 v254, s5, 14
	s_add_u32 s4, s0, 0xe0c00
	s_addc_u32 s5, s1, 0
	v_writelane_b32 v254, s4, 15
	v_mov_b64_e32 v[252:253], 0x100
	s_mov_b32 s85, 0x5040100
	v_writelane_b32 v254, s5, 16
	s_add_u32 s4, s0, 0xe0d00
	s_addc_u32 s5, s1, 0
	v_writelane_b32 v254, s4, 17
	s_mov_b64 s[10:11], 0x80
	s_mov_b32 s26, 1.0
	v_writelane_b32 v254, s5, 18
	s_add_u32 s4, s0, 0xe0e00
	s_addc_u32 s5, s1, 0
	v_writelane_b32 v254, s4, 19
	s_mov_b64 s[28:29], 0x20000
	s_nop 0
	v_writelane_b32 v254, s5, 20
	s_add_u32 s4, s0, 0xe0f00
	s_addc_u32 s5, s1, 0
	v_writelane_b32 v254, s4, 21
	s_nop 1
	v_writelane_b32 v254, s5, 22
	s_add_u32 s4, s0, 0xe1000
	s_addc_u32 s5, s1, 0
	v_writelane_b32 v254, s4, 23
	s_nop 1
	v_writelane_b32 v254, s5, 24
	s_add_u32 s4, s0, 0xe1100
	s_addc_u32 s5, s1, 0
	v_writelane_b32 v254, s4, 25
	s_nop 1
	v_writelane_b32 v254, s5, 26
	s_add_u32 s4, s0, 0xe1200
	s_addc_u32 s5, s1, 0
	v_writelane_b32 v254, s4, 27
	s_nop 1
	v_writelane_b32 v254, s5, 28
	s_add_u32 s4, s0, 0xe1300
	s_addc_u32 s5, s1, 0
	v_writelane_b32 v254, s4, 29
	s_cmp_eq_u32 s16, 15
	s_nop 0
	v_writelane_b32 v254, s5, 30
	s_cselect_b64 s[4:5], -1, 0
	v_writelane_b32 v254, s4, 31
	s_cmp_eq_u32 s16, 14
	s_nop 0
	v_writelane_b32 v254, s5, 32
	s_cselect_b64 s[4:5], -1, 0
	v_writelane_b32 v254, s4, 33
	s_cmp_eq_u32 s16, 13
	s_nop 0
	v_writelane_b32 v254, s5, 34
	s_cselect_b64 s[4:5], -1, 0
	v_writelane_b32 v254, s4, 35
	s_cmp_eq_u32 s16, 12
	s_nop 0
	v_writelane_b32 v254, s5, 36
	s_cselect_b64 s[4:5], -1, 0
	v_writelane_b32 v254, s4, 37
	s_cmp_eq_u32 s16, 11
	s_nop 0
	v_writelane_b32 v254, s5, 38
	s_cselect_b64 s[4:5], -1, 0
	v_writelane_b32 v254, s4, 39
	s_cmp_eq_u32 s16, 10
	s_nop 0
	v_writelane_b32 v254, s5, 40
	s_cselect_b64 s[4:5], -1, 0
	v_writelane_b32 v254, s4, 41
	s_cmp_eq_u32 s16, 9
	s_nop 0
	v_writelane_b32 v254, s5, 42
	s_cselect_b64 s[4:5], -1, 0
	v_writelane_b32 v254, s4, 43
	s_cmp_eq_u32 s16, 8
	s_nop 0
	v_writelane_b32 v254, s5, 44
	s_cselect_b64 s[4:5], -1, 0
	v_writelane_b32 v254, s4, 45
	s_cmp_eq_u32 s16, 7
	s_nop 0
	v_writelane_b32 v254, s5, 46
	s_cselect_b64 s[4:5], -1, 0
	v_writelane_b32 v254, s4, 47
	s_cmp_eq_u32 s16, 6
	s_nop 0
	v_writelane_b32 v254, s5, 48
	s_cselect_b64 s[4:5], -1, 0
	v_writelane_b32 v254, s4, 49
	s_cmp_eq_u32 s16, 5
	s_nop 0
	v_writelane_b32 v254, s5, 50
	s_cselect_b64 s[4:5], -1, 0
	v_writelane_b32 v254, s4, 51
	s_cmp_eq_u32 s16, 4
	s_nop 0
	v_writelane_b32 v254, s5, 52
	s_cselect_b64 s[4:5], -1, 0
	v_writelane_b32 v254, s4, 53
	s_cmp_eq_u32 s16, 3
	s_nop 0
	v_writelane_b32 v254, s5, 54
	s_cselect_b64 s[4:5], -1, 0
	v_writelane_b32 v254, s4, 55
	s_cmp_eq_u32 s16, 2
	s_nop 0
	v_writelane_b32 v254, s5, 56
	s_cselect_b64 s[4:5], -1, 0
	v_writelane_b32 v254, s4, 57
	s_cmp_eq_u32 s16, 1
	s_nop 0
	v_writelane_b32 v254, s5, 58
	s_cselect_b64 s[4:5], -1, 0
	v_writelane_b32 v254, s4, 59
	s_cmp_eq_u32 s16, 0
	s_nop 0
	v_writelane_b32 v254, s5, 60
	s_cselect_b64 s[4:5], -1, 0
	v_writelane_b32 v254, s4, 61
	s_nop 1
	v_writelane_b32 v254, s5, 62
	s_lshl_b32 s4, s16, 8
	s_add_u32 s2, s2, s4
	s_addc_u32 s3, s3, 0
	s_add_u32 s4, s2, 0x1400
	s_addc_u32 s5, s3, 0
	s_add_u32 s78, s2, 0x2400
	s_addc_u32 s79, s3, 0
	s_add_u32 s2, s0, 0xe3400
	v_writelane_b32 v254, s4, 63
	s_addc_u32 s3, s1, 0
	s_add_u32 s88, s0, 0xe3500
	v_writelane_b32 v255, s5, 0
	v_writelane_b32 v255, s2, 1
	s_addc_u32 s89, s1, 0
	s_add_i32 s0, 0, 0x23fc0
	v_writelane_b32 v255, s3, 2
	v_writelane_b32 v255, s0, 3
	s_add_i32 s0, 0, 0x23fc4
	v_writelane_b32 v255, s0, 4
	s_add_i32 s0, 0, 0x10800
	v_writelane_b32 v255, s0, 5
	v_cmp_eq_u32_e64 s[0:1], 0, v0
	s_nop 1
	v_writelane_b32 v255, s0, 6
	s_nop 1
	v_writelane_b32 v255, s1, 7
	s_mov_b32 s0, s9
	v_writelane_b32 v255, s0, 8
	s_nop 1
	v_writelane_b32 v255, s1, 9
	v_writelane_b32 v255, s94, 10
	s_nop 1
	v_writelane_b32 v255, s95, 11
	v_writelane_b32 v255, s84, 12
	v_writelane_b32 v255, s96, 13
	s_nop 1
	v_writelane_b32 v255, s97, 14
	v_writelane_b32 v255, s78, 15
	s_nop 1
	v_writelane_b32 v255, s79, 16
	v_writelane_b32 v255, s88, 17
	s_nop 1
	v_writelane_b32 v255, s89, 18
	v_writelane_b32 v255, s83, 19
	v_writelane_b32 v255, s90, 20
	s_nop 1
	v_writelane_b32 v255, s91, 21
	v_writelane_b32 v255, s92, 22
	s_nop 1
	v_writelane_b32 v255, s93, 23
	v_writelane_b32 v255, s86, 24
	s_nop 1
	v_writelane_b32 v255, s87, 25
	s_branch .LBB0_159

.LBB0_254:
	v_readlane_b32 s0, v254, 2
	s_add_i32 s4, s0, 1
	s_cmp_ge_i32 s4, s81
	s_cbranch_scc1 .LBB0_362
	v_readlane_b32 s100, v255, 57
	s_cmp_lg_u32 s100, 0
	s_cbranch_scc0 .Lgq_orig_win
	s_waitcnt vmcnt(0) lgkmcnt(0)
	s_barrier
	v_readlane_b32 s100, v255, 59
	s_add_i32 s100, s100, 1
	v_writelane_b32 v255, s100, 59
	v_cmp_eq_u32_e32 vcc, 0, v215
	s_and_saveexec_b64 s[0:1], vcc
	s_cbranch_execz .Lgq_w_win
	s_load_dwordx2 s[2:3], s[94:95], 0xb8
	v_readlane_b32 s101, v255, 12
	s_and_b32 s101, s101, 63
	s_lshl_b32 s101, s101, 6
	s_cmp_lt_u32 s101, 0x800
	s_movk_i32 s7, 0x1400
	s_cselect_b32 s7, 0xc00, s7
	s_add_i32 s101, s101, s7
	s_lshl_b32 s100, s100, 2
	v_mov_b32_e32 v0, s101
	v_mov_b32_e32 v1, 1
	s_waitcnt lgkmcnt(0)
	s_add_u32 s2, s2, 0xe0000
	s_addc_u32 s3, s3, 0
	global_atomic_add v0, v1, s[2:3]
	buffer_inv sc1
	s_mov_b32 s6, 0

.Lgq_orig_win:
	v_readlane_b32 s0, v254, 3
	v_readlane_b32 s1, v254, 4
	s_andn2_b64 vcc, exec, s[0:1]
	s_cbranch_vccnz .LBB0_267
	s_waitcnt lgkmcnt(0)
	s_barrier
	s_mov_b64 s[0:1], exec
	v_readlane_b32 s2, v255, 6
	v_readlane_b32 s3, v255, 7
	s_and_b64 s[2:3], s[0:1], s[2:3]
	s_mov_b64 exec, s[2:3]
	s_cbranch_execz .LBB0_266
	v_readlane_b32 s2, v254, 0
	v_readlane_b32 s3, v254, 1
	buffer_wbl2 sc1
	s_waitcnt vmcnt(0)
	s_load_dwordx2 s[2:3], s[2:3], 0x58
	s_mov_b64 s[6:7], exec
	v_mbcnt_lo_u32_b32 v1, s6, 0
	v_mbcnt_hi_u32_b32 v1, s7, v1
	v_cmp_eq_u32_e32 vcc, 0, v1
	s_waitcnt lgkmcnt(0)
	global_load_dword v0, v213, s[2:3] offset:40
	s_and_saveexec_b64 s[12:13], vcc
	s_cbranch_execz .LBB0_259
	s_bcnt1_i32_b64 s5, s[6:7]
	v_mov_b32_e32 v2, s5
	global_atomic_add v2, v213, v2, s[2:3] offset:32 sc0

; __global__ void __launch_bounds__(NWAVES * 64, 2) fwd_kernel(Args args) {
;     ...
;                 const int fr = lane & 15, fq = lane >> 4;
;                 const int sr = tid >> 2, spart = tid & 3, ccs = (tid & 31) * 8;
;                 int last_g = -1;
;                 float zf_ = 0.f; asm volatile("" : "+v"(zf_)); const f32x4 zero4 = {zf_, zf_, zf_, zf_};
;                 v4u raw[8]; f32x2 stp[8]; f32x4 ga, gb, ba, bb;
;                 ga = gb = ba = bb = zero4;
;     ...
;                 { const int it0_ = bx < 1024 ? bx : 0; SP_PREFETCH(it0_); }
.LBB0_364:
	s_andn2_b64 vcc, exec, s[0:1]
	s_cbranch_vccnz .LBB0_442
	s_waitcnt vmcnt(0) lgkmcnt(0)
	v_mov_b32_e32 v21, v215
	s_mov_b32 s4, s82
	s_and_b32 s100, s84, 7
	s_lshl_b32 s100, s100, 3
	s_bfe_u32 s101, s84, 0x30003
	s_add_i32 s100, s100, s101
	s_lshl_b32 s100, s100, 4
	s_lshr_b32 s101, s84, 6
	s_lshl_b32 s101, s101, 1
	s_add_i32 s19, s100, s101
	s_mov_b32 s100, 0
	s_mov_b64 s[0:1], s[94:95]
	v_readfirstlane_b32 s5, v21
	v_mov_b32_e32 v0, v213
	s_cmpk_gt_i32 s19, 0x3ff
	s_cbranch_scc1 .LBB0_376
	v_readlane_b32 s2, v255, 8
	v_readlane_b32 s3, v255, 9
	s_mul_hi_u32 s2, s2, 0xaaaaaaab
	s_lshr_b32 s8, s2, 1
	s_load_dwordx4 s[40:43], s[0:1], 0x80
	s_load_dwordx2 s[2:3], s[0:1], 0xb8
	s_lshl_b64 s[6:7], s[8:9], 12
	v_ashrrev_i32_e32 v141, 2, v21
	v_lshlrev_b32_e32 v1, 3, v21
	v_and_b32_e32 v20, 0xf8, v1
	s_waitcnt lgkmcnt(0)
	s_add_u32 s16, s2, 0x13c00000
	s_addc_u32 s17, s3, 0
	s_lshl_b64 s[14:15], s[8:9], 13
	s_add_u32 s12, s40, s14
	s_addc_u32 s13, s41, s15
	s_lshl_b32 s8, s19, 4
	s_and_b32 s18, s8, 0xffffff80
	v_add_u32_e32 v1, 0x800, v21
	v_add_u32_e32 v4, s18, v141
	v_ashrrev_i32_e32 v189, 5, v1
	v_add_u32_e32 v1, 0xa00, v21
	v_ashrrev_i32_e32 v5, 31, v4
	v_ashrrev_i32_e32 v201, 5, v1
	v_add_u32_e32 v1, 0xc00, v21
	v_and_b32_e32 v29, 3, v21
	v_lshlrev_b64 v[4:5], 8, v[4:5]
	v_ashrrev_i32_e32 v211, 5, v1
	v_add_u32_e32 v1, 0xe00, v21
	v_lshlrev_b32_e32 v212, 6, v29
	v_lshl_add_u64 v[4:5], s[16:17], 0, v[4:5]
	v_ashrrev_i32_e32 v230, 5, v1
	v_lshl_add_u64 v[4:5], v[4:5], 0, v[212:213]
	global_load_dwordx4 v[52:55], v[4:5], off offset:48
	global_load_dwordx4 v[56:59], v[4:5], off offset:32
	global_load_dwordx4 v[60:63], v[4:5], off offset:16
	global_load_dwordx4 v[64:67], v[4:5], off
	v_add_u32_e32 v4, s18, v230
	v_ashrrev_i32_e32 v5, 31, v4
	v_lshlrev_b64 v[4:5], 13, v[4:5]
	s_lshl_b32 s8, s19, 9
	s_waitcnt vmcnt(13)
; #define LAS __attribute__((address_space(3)))
; __global__ void __launch_bounds__(NWAVES * 64, 2) fwd_kernel(Args args) {
;     ...
;                 LAS f32x2* ms = (LAS f32x2*)L;
;                 LAS unsigned char* vn = L + 1024;
;                 LAS unsigned char* wsl = L + 67584;
;                 const float* lng = A_->gm_ln_g + (size_t)jl * 2048; const float* lnb = A_->gm_ln_b + (size_t)jl * 2048;
;                 const int fr = lane & 15, fq = lane >> 4;
;                 const int sr = tid >> 2, spart = tid & 3, ccs = (tid & 31) * 8;
;                 int last_g = -1;
;                 float zf_ = 0.f; asm volatile("" : "+v"(zf_)); const f32x4 zero4 = {zf_, zf_, zf_, zf_};
;                 v4u raw[8]; f32x2 stp[8]; f32x4 ga, gb, ba, bb;
;                 ga = gb = ba = bb = zero4;
;     ...
;                 { const int it0_ = bx < 1024 ? bx : 0; SP_PREFETCH(it0_); }
	v_add_u32_e32 v6, s18, v211
	v_lshl_add_u64 v[4:5], s[2:3], 0, v[4:5]
	s_and_b32 s8, s8, 0xe00
	v_ashrrev_i32_e32 v7, 31, v6
	v_lshl_add_u64 v[142:143], s[16:17], 0, v[212:213]
	v_lshl_add_u64 v[4:5], v[4:5], 0, s[8:9]
	v_lshlrev_b32_e32 v212, 1, v20
	v_lshlrev_b64 v[6:7], 13, v[6:7]
	v_add_u32_e32 v12, s18, v201
	v_lshl_add_u64 v[4:5], v[4:5], 0, v[212:213]
	s_mov_b32 s16, 0x7801000
	v_lshl_add_u64 v[6:7], s[2:3], 0, v[6:7]
	v_ashrrev_i32_e32 v13, 31, v12
	v_add_u32_e32 v28, 0x600, v21
	v_add_co_u32_e32 v4, vcc, s16, v4
	v_lshl_add_u64 v[6:7], v[6:7], 0, s[8:9]
	v_lshlrev_b64 v[12:13], 13, v[12:13]
	v_add_u32_e32 v14, s18, v189
	v_ashrrev_i32_e32 v181, 5, v28
	v_addc_co_u32_e32 v5, vcc, 0, v5, vcc
	v_lshl_add_u64 v[6:7], v[6:7], 0, v[212:213]
	v_lshl_add_u64 v[12:13], s[2:3], 0, v[12:13]
	v_ashrrev_i32_e32 v15, 31, v14
	v_add_u32_e32 v27, 0x400, v21
	v_add_co_u32_e32 v8, vcc, s16, v6
	v_lshl_add_u64 v[12:13], v[12:13], 0, s[8:9]
	v_lshlrev_b64 v[14:15], 13, v[14:15]
	v_add_u32_e32 v22, s18, v181
	v_ashrrev_i32_e32 v171, 5, v27
	v_addc_co_u32_e32 v9, vcc, 0, v7, vcc
	v_lshl_add_u64 v[12:13], v[12:13], 0, v[212:213]
	v_lshl_add_u64 v[14:15], s[2:3], 0, v[14:15]
	v_ashrrev_i32_e32 v23, 31, v22
	v_add_co_u32_e32 v12, vcc, s16, v12
	v_lshl_add_u64 v[14:15], v[14:15], 0, s[8:9]
	v_lshlrev_b64 v[22:23], 13, v[22:23]
	v_add_u32_e32 v24, s18, v171
	v_addc_co_u32_e32 v13, vcc, 0, v13, vcc
	v_lshl_add_u64 v[14:15], v[14:15], 0, v[212:213]
	v_lshl_add_u64 v[22:23], s[2:3], 0, v[22:23]
	v_ashrrev_i32_e32 v25, 31, v24
	v_add_co_u32_e32 v16, vcc, s16, v14
	v_lshl_add_u64 v[22:23], v[22:23], 0, s[8:9]
	v_lshlrev_b64 v[24:25], 13, v[24:25]
	v_addc_co_u32_e32 v17, vcc, 0, v15, vcc
	v_lshl_add_u64 v[22:23], v[22:23], 0, v[212:213]
	v_lshl_add_u64 v[24:25], s[2:3], 0, v[24:25]
	v_add_co_u32_e32 v22, vcc, s16, v22
	v_lshl_add_u64 v[24:25], v[24:25], 0, s[8:9]
	v_add_u32_e32 v26, 0x200, v21
	v_addc_co_u32_e32 v23, vcc, 0, v23, vcc
	v_lshl_add_u64 v[24:25], v[24:25], 0, v[212:213]
	v_ashrrev_i32_e32 v163, 5, v26
	v_add_co_u32_e32 v24, vcc, s16, v24
	global_load_dwordx4 v[4:7], v[4:5], off
	s_nop 0
	global_load_dwordx4 v[8:11], v[8:9], off
	s_nop 0
	global_load_dwordx4 v[12:15], v[12:13], off
	s_nop 0
	global_load_dwordx4 v[16:19], v[16:17], off
	v_addc_co_u32_e32 v25, vcc, 0, v25, vcc
	global_load_dwordx4 v[36:39], v[22:23], off
	global_load_dwordx4 v[40:43], v[24:25], off
	v_add_u32_e32 v22, s18, v163
	v_ashrrev_i32_e32 v161, 5, v21
	v_ashrrev_i32_e32 v23, 31, v22
	v_lshlrev_b64 v[22:23], 13, v[22:23]
	v_add_u32_e32 v24, s18, v161
	v_lshl_add_u64 v[22:23], s[2:3], 0, v[22:23]
	v_ashrrev_i32_e32 v25, 31, v24
	v_lshl_add_u64 v[22:23], v[22:23], 0, s[8:9]
	v_lshlrev_b64 v[24:25], 13, v[24:25]
	v_lshl_add_u64 v[22:23], v[22:23], 0, v[212:213]
	v_lshl_add_u64 v[24:25], s[2:3], 0, v[24:25]
	v_add_co_u32_e32 v22, vcc, s16, v22
	v_lshl_add_u64 v[24:25], v[24:25], 0, s[8:9]
	s_nop 0
	v_addc_co_u32_e32 v23, vcc, 0, v23, vcc
	v_lshl_add_u64 v[24:25], v[24:25], 0, v[212:213]
	v_add_co_u32_e32 v24, vcc, s16, v24
	v_and_b32_e32 v140, 15, v21
	s_nop 0
	v_addc_co_u32_e32 v25, vcc, 0, v25, vcc
	global_load_dwordx4 v[44:47], v[22:23], off
	global_load_dwordx4 v[48:51], v[24:25], off
	v_and_b32_e32 v23, 64, v246
	v_xor_b32_e32 v22, 1, v246
	v_add_u32_e32 v23, 64, v23
	v_cmp_lt_i32_e32 vcc, v22, v23
	s_add_u32 s14, s42, s14
	s_mov_b64 s[16:17], 0x5400000
	v_cndmask_b32_e32 v22, v246, v22, vcc
	v_lshlrev_b32_e32 v231, 2, v22
	v_xor_b32_e32 v22, 2, v246
	v_cmp_lt_i32_e32 vcc, v22, v23
	v_mov_b32_e32 v23, v213
	v_readlane_b32 s8, v255, 5
	v_cndmask_b32_e32 v22, v246, v22, vcc
	v_lshlrev_b32_e32 v232, 2, v22
	v_lshlrev_b32_e32 v22, 4, v140
	v_lshl_add_u64 v[24:25], s[2:3], 0, v[22:23]
	s_addc_u32 s15, s43, s15
	v_lshl_add_u64 v[144:145], v[24:25], 0, s[16:17]
	v_add_u32_e32 v24, s8, v22
	v_lshlrev_b32_e32 v22, 2, v20
	s_ashr_i32 s8, s5, 1
	v_lshl_add_u64 v[146:147], s[12:13], 0, v[22:23]
	s_and_b32 s12, s8, 0xffffffe0
	s_ashr_i32 s13, s12, 31
	v_lshl_add_u64 v[148:149], s[14:15], 0, v[22:23]
	s_lshl_b64 s[14:15], s[12:13], 1
	v_bfe_u32 v30, v21, 4, 2
	s_add_u32 s14, s2, s14
	v_add_u32_e32 v25, 0, v212
	s_addc_u32 s15, s3, s15
	v_lshlrev_b32_e32 v212, 3, v30
	v_lshl_add_u64 v[22:23], s[14:15], 0, v[212:213]
	s_mov_b64 s[14:15], 0x7800000
	v_lshl_add_u64 v[150:151], v[22:23], 0, s[14:15]
	v_ashrrev_i32_e32 v22, 4, v21
	v_ashrrev_i32_e32 v23, 31, v22
	s_movk_i32 s8, 0x110
	v_lshlrev_b64 v[152:153], 8, v[22:23]
	v_mul_lo_u32 v21, v22, s8
	v_ashrrev_i32_e32 v22, 4, v26
	v_ashrrev_i32_e32 v23, 31, v22
	v_lshl_or_b32 v233, v30, 2, s12
	s_add_u32 s12, s2, 0xfc00000
	v_lshlrev_b64 v[154:155], 8, v[22:23]
	v_mul_lo_u32 v26, v22, s8
	v_ashrrev_i32_e32 v22, 4, v27
	v_cmp_eq_u32_e64 s[38:39], 0, v29
	v_lshlrev_b32_e32 v29, 4, v30
	s_addc_u32 s13, s3, 0
	v_ashrrev_i32_e32 v23, 31, v22
	s_andn2_b32 s5, s5, 63
	v_lshlrev_b64 v[156:157], 8, v[22:23]
	v_mul_lo_u32 v27, v22, s8
	v_ashrrev_i32_e32 v22, 4, v28
	s_movk_i32 s14, 0x204
	v_mad_u32_u24 v234, v140, s8, v29
	v_mov_b32_e32 v29, s5
	s_movk_i32 s5, 0x1020
	v_mov_b32_e32 v2, v0
	v_mov_b32_e32 v3, v0
	v_ashrrev_i32_e32 v23, 31, v22
	v_mul_lo_u32 v68, v230, s14
	v_mad_u32_u24 v29, v30, s5, v29
	v_mov_b32_e32 v1, v0
	v_lshlrev_b64 v[158:159], 8, v[22:23]
	v_mul_lo_u32 v22, v22, s8
	v_mul_lo_u32 v23, v161, s14
	v_mul_lo_u32 v28, v163, s14
	v_mul_lo_u32 v31, v171, s14
	v_mul_lo_u32 v32, v181, s14
	v_mul_lo_u32 v33, v189, s14
	v_mul_lo_u32 v34, v201, s14
	v_mul_lo_u32 v35, v211, s14
	v_lshl_or_b32 v29, v140, 1, v29
	v_add_u32_e32 v249, v25, v68
	v_mov_b64_e32 v[70:71], v[2:3]
	v_mov_b64_e32 v[74:75], v[2:3]
	v_mov_b64_e32 v[78:79], v[2:3]
	v_mov_b64_e32 v[82:83], v[2:3]
	s_mov_b32 s20, -1
	v_add_u32_e32 v235, 0x400, v29
	v_add_u32_e32 v236, v24, v21
	v_add_u32_e32 v237, v24, v26
	v_add_u32_e32 v238, v24, v27
	v_add_u32_e32 v239, v24, v22
	v_add_u32_e32 v240, v25, v23
	v_add_u32_e32 v241, v25, v28
	v_add_u32_e32 v242, v25, v31
	v_add_u32_e32 v243, v25, v32
	v_add_u32_e32 v244, v25, v33
	v_add_u32_e32 v245, v25, v34
	v_add_u32_e32 v248, v25, v35
	v_lshlrev_b32_e32 v250, 2, v140
	v_lshlrev_b32_e32 v212, 1, v20
	v_mov_b64_e32 v[68:69], v[0:1]
	v_mov_b64_e32 v[72:73], v[0:1]
	v_mov_b64_e32 v[76:77], v[0:1]
	v_mov_b64_e32 v[80:81], v[0:1]

; #define LAS __attribute__((address_space(3)))
; __device__ __forceinline__ unsigned pk2(float lo, float hi) { return pg8::cvt_pk_bf16(lo, hi); }
; __device__ __forceinline__ float bf_lo(unsigned w) { return __uint_as_float(w << 16); }
; __device__ __forceinline__ float bf_hi(unsigned w) { return __uint_as_float(w & 0xffff0000u); }
; __global__ void __launch_bounds__(NWAVES * 64, 2) fwd_kernel(Args args) {
;     ...
;                     __syncthreads();
; #pragma unroll
;                     for (int i = 0; i < 8; ++i) { const int p = (tid + 512 * i) >> 5;
;                         const f32x2 m2 = ms[p]; const v4u rw = raw[i];
;                         const float y0 = (bf_lo(rw.x) - m2[0]) * m2[1] * ga[0] + ba[0], y1 = (bf_hi(rw.x) - m2[0]) * m2[1] * ga[1] + ba[1];
;                         const float y2 = (bf_lo(rw.y) - m2[0]) * m2[1] * ga[2] + ba[2], y3 = (bf_hi(rw.y) - m2[0]) * m2[1] * ga[3] + ba[3];
;                         const float y4 = (bf_lo(rw.z) - m2[0]) * m2[1] * gb[0] + bb[0], y5 = (bf_hi(rw.z) - m2[0]) * m2[1] * gb[1] + bb[1];
;                         const float y6 = (bf_lo(rw.w) - m2[0]) * m2[1] * gb[2] + bb[2], y7 = (bf_hi(rw.w) - m2[0]) * m2[1] * gb[3] + bb[3];
;                         LAS unsigned* dst = (LAS unsigned*)(vn + p * 516 + ccs * 2);
;                         dst[0] = pk2(y0, y1); dst[1] = pk2(y2, y3); dst[2] = pk2(y4, y5); dst[3] = pk2(y6, y7); }
.LBB0_373:
	v_lshl_add_u32 v1, v161, 3, 0
	s_waitcnt lgkmcnt(0)
	s_barrier
	ds_read_b64 v[2:3], v1
	s_waitcnt vmcnt(0)
	v_lshlrev_b32_e32 v1, 16, v48
	v_and_b32_e32 v48, 0xffff0000, v48
	v_lshlrev_b32_e32 v52, 16, v49
	v_and_b32_e32 v49, 0xffff0000, v49
	s_waitcnt lgkmcnt(0)
	v_sub_f32_e32 v1, v1, v2
	v_mul_f32_e32 v1, v3, v1
	v_sub_f32_e32 v48, v48, v2
	v_fma_f32 v1, v24, v1, v32
	v_mul_f32_e32 v48, v3, v48
	v_sub_f32_e32 v52, v52, v2
	v_sub_f32_e32 v49, v49, v2
	v_lshlrev_b32_e32 v53, 16, v50
	v_and_b32_e32 v50, 0xffff0000, v50
	v_fma_f32 v48, v25, v48, v33
	v_mul_f32_e32 v52, v3, v52
	v_mul_f32_e32 v49, v3, v49
	v_sub_f32_e32 v53, v53, v2
	v_sub_f32_e32 v50, v50, v2
	v_lshlrev_b32_e32 v54, 16, v51
	v_and_b32_e32 v51, 0xffff0000, v51
	v_cvt_pk_bf16_f32 v1, v1, v48
	v_fma_f32 v52, v26, v52, v34
	v_fma_f32 v49, v27, v49, v35
	v_mul_f32_e32 v53, v3, v53
	v_mul_f32_e32 v50, v3, v50
	v_sub_f32_e32 v54, v54, v2
	v_sub_f32_e32 v2, v51, v2
	ds_write_b32 v240, v1 offset:1024
	v_cvt_pk_bf16_f32 v1, v52, v49
	v_fma_f32 v53, v20, v53, v28
	v_fma_f32 v50, v21, v50, v29
	v_mul_f32_e32 v54, v3, v54
	v_mul_f32_e32 v2, v3, v2
	ds_write_b32 v240, v1 offset:1028
	v_cvt_pk_bf16_f32 v1, v53, v50
	v_fma_f32 v54, v22, v54, v30
	v_fma_f32 v2, v23, v2, v31
	ds_write_b32 v240, v1 offset:1032
	v_cvt_pk_bf16_f32 v1, v54, v2
	ds_write_b32 v240, v1 offset:1036
	v_lshl_add_u32 v1, v163, 3, 0
	ds_read_b64 v[2:3], v1
	v_lshlrev_b32_e32 v1, 16, v44
	v_and_b32_e32 v44, 0xffff0000, v44
	v_lshlrev_b32_e32 v48, 16, v45
	v_and_b32_e32 v45, 0xffff0000, v45
	s_waitcnt lgkmcnt(0)
	v_sub_f32_e32 v1, v1, v2
	v_mul_f32_e32 v1, v3, v1
	v_sub_f32_e32 v44, v44, v2
	v_fma_f32 v1, v24, v1, v32
	v_mul_f32_e32 v44, v3, v44
	v_sub_f32_e32 v48, v48, v2
	v_sub_f32_e32 v45, v45, v2
	v_lshlrev_b32_e32 v49, 16, v46
	v_and_b32_e32 v46, 0xffff0000, v46
	v_fma_f32 v44, v25, v44, v33
	v_mul_f32_e32 v48, v3, v48
	v_mul_f32_e32 v45, v3, v45
	v_sub_f32_e32 v49, v49, v2
	v_sub_f32_e32 v46, v46, v2
	v_lshlrev_b32_e32 v50, 16, v47
	v_and_b32_e32 v47, 0xffff0000, v47
	v_cvt_pk_bf16_f32 v1, v1, v44
	v_fma_f32 v48, v26, v48, v34
	v_fma_f32 v45, v27, v45, v35
	v_mul_f32_e32 v49, v3, v49
	v_mul_f32_e32 v46, v3, v46
	v_sub_f32_e32 v50, v50, v2
	v_sub_f32_e32 v2, v47, v2
	ds_write_b32 v241, v1 offset:1024
	v_cvt_pk_bf16_f32 v1, v48, v45
	v_fma_f32 v49, v20, v49, v28
	v_fma_f32 v46, v21, v46, v29
	v_mul_f32_e32 v50, v3, v50
	v_mul_f32_e32 v2, v3, v2
	ds_write_b32 v241, v1 offset:1028
	v_cvt_pk_bf16_f32 v1, v49, v46
	v_fma_f32 v50, v22, v50, v30
	v_fma_f32 v2, v23, v2, v31
	ds_write_b32 v241, v1 offset:1032
	v_cvt_pk_bf16_f32 v1, v50, v2
	ds_write_b32 v241, v1 offset:1036
	v_lshl_add_u32 v1, v171, 3, 0
	ds_read_b64 v[2:3], v1
	v_lshlrev_b32_e32 v1, 16, v40
	v_and_b32_e32 v40, 0xffff0000, v40
	v_lshlrev_b32_e32 v44, 16, v41
	v_and_b32_e32 v41, 0xffff0000, v41
	s_waitcnt lgkmcnt(0)
	v_sub_f32_e32 v1, v1, v2
	v_mul_f32_e32 v1, v3, v1
	v_sub_f32_e32 v40, v40, v2
	v_fma_f32 v1, v24, v1, v32
	v_mul_f32_e32 v40, v3, v40
	v_sub_f32_e32 v44, v44, v2
	v_sub_f32_e32 v41, v41, v2
	v_lshlrev_b32_e32 v45, 16, v42
	v_and_b32_e32 v42, 0xffff0000, v42
	v_fma_f32 v40, v25, v40, v33
	v_mul_f32_e32 v44, v3, v44
	v_mul_f32_e32 v41, v3, v41
	v_sub_f32_e32 v45, v45, v2
	v_sub_f32_e32 v42, v42, v2
	v_lshlrev_b32_e32 v46, 16, v43
	v_and_b32_e32 v43, 0xffff0000, v43
	v_cvt_pk_bf16_f32 v1, v1, v40
	v_fma_f32 v44, v26, v44, v34
	v_fma_f32 v41, v27, v41, v35
	v_mul_f32_e32 v45, v3, v45
	v_mul_f32_e32 v42, v3, v42
	v_sub_f32_e32 v46, v46, v2
	v_sub_f32_e32 v2, v43, v2
	ds_write_b32 v242, v1 offset:1024
	v_cvt_pk_bf16_f32 v1, v44, v41
	v_fma_f32 v45, v20, v45, v28
	v_fma_f32 v42, v21, v42, v29
	v_mul_f32_e32 v46, v3, v46
	v_mul_f32_e32 v2, v3, v2
	ds_write_b32 v242, v1 offset:1028
	v_cvt_pk_bf16_f32 v1, v45, v42
	v_fma_f32 v46, v22, v46, v30
	v_fma_f32 v2, v23, v2, v31
	ds_write_b32 v242, v1 offset:1032
	v_cvt_pk_bf16_f32 v1, v46, v2
	ds_write_b32 v242, v1 offset:1036
	v_lshl_add_u32 v1, v181, 3, 0
	ds_read_b64 v[2:3], v1
	v_lshlrev_b32_e32 v1, 16, v36
	v_and_b32_e32 v36, 0xffff0000, v36
	v_lshlrev_b32_e32 v40, 16, v37
	v_and_b32_e32 v37, 0xffff0000, v37
	s_waitcnt lgkmcnt(0)
	v_sub_f32_e32 v1, v1, v2
	v_mul_f32_e32 v1, v3, v1
	v_sub_f32_e32 v36, v36, v2
	v_fma_f32 v1, v24, v1, v32
	v_mul_f32_e32 v36, v3, v36
	v_sub_f32_e32 v40, v40, v2
	v_sub_f32_e32 v37, v37, v2
	v_lshlrev_b32_e32 v41, 16, v38
	v_and_b32_e32 v38, 0xffff0000, v38
	v_fma_f32 v36, v25, v36, v33
	v_mul_f32_e32 v40, v3, v40
	v_mul_f32_e32 v37, v3, v37
	v_sub_f32_e32 v41, v41, v2
	v_sub_f32_e32 v38, v38, v2
	v_lshlrev_b32_e32 v42, 16, v39
	v_and_b32_e32 v39, 0xffff0000, v39
	v_cvt_pk_bf16_f32 v1, v1, v36
	v_fma_f32 v40, v26, v40, v34
	v_fma_f32 v37, v27, v37, v35
	v_mul_f32_e32 v41, v3, v41
	v_mul_f32_e32 v38, v3, v38
	v_sub_f32_e32 v42, v42, v2
	v_sub_f32_e32 v2, v39, v2
	ds_write_b32 v243, v1 offset:1024
	v_cvt_pk_bf16_f32 v1, v40, v37
	v_fma_f32 v41, v20, v41, v28
	v_fma_f32 v38, v21, v38, v29
	v_mul_f32_e32 v42, v3, v42
	v_mul_f32_e32 v2, v3, v2
	ds_write_b32 v243, v1 offset:1028
	v_cvt_pk_bf16_f32 v1, v41, v38
	v_fma_f32 v42, v22, v42, v30
	v_fma_f32 v2, v23, v2, v31
	ds_write_b32 v243, v1 offset:1032
	v_cvt_pk_bf16_f32 v1, v42, v2
	ds_write_b32 v243, v1 offset:1036
	v_lshl_add_u32 v1, v189, 3, 0
	ds_read_b64 v[2:3], v1
	v_lshlrev_b32_e32 v1, 16, v16
	v_and_b32_e32 v16, 0xffff0000, v16
	v_lshlrev_b32_e32 v36, 16, v17
	v_and_b32_e32 v17, 0xffff0000, v17
	s_waitcnt lgkmcnt(0)
; #define LAS __attribute__((address_space(3)))
; __device__ __forceinline__ unsigned pk2(float lo, float hi) { return pg8::cvt_pk_bf16(lo, hi); }
; __device__ __forceinline__ float bf_lo(unsigned w) { return __uint_as_float(w << 16); }
; __device__ __forceinline__ float bf_hi(unsigned w) { return __uint_as_float(w & 0xffff0000u); }
; __global__ void __launch_bounds__(NWAVES * 64, 2) fwd_kernel(Args args) {
;     ...
;                     for (int i = 0; i < 8; ++i) { const int p = (tid + 512 * i) >> 5;
;                         const f32x2 m2 = ms[p]; const v4u rw = raw[i];
;                         const float y0 = (bf_lo(rw.x) - m2[0]) * m2[1] * ga[0] + ba[0], y1 = (bf_hi(rw.x) - m2[0]) * m2[1] * ga[1] + ba[1];
;                         const float y2 = (bf_lo(rw.y) - m2[0]) * m2[1] * ga[2] + ba[2], y3 = (bf_hi(rw.y) - m2[0]) * m2[1] * ga[3] + ba[3];
;                         const float y4 = (bf_lo(rw.z) - m2[0]) * m2[1] * gb[0] + bb[0], y5 = (bf_hi(rw.z) - m2[0]) * m2[1] * gb[1] + bb[1];
;                         const float y6 = (bf_lo(rw.w) - m2[0]) * m2[1] * gb[2] + bb[2], y7 = (bf_hi(rw.w) - m2[0]) * m2[1] * gb[3] + bb[3];
;                         LAS unsigned* dst = (LAS unsigned*)(vn + p * 516 + ccs * 2);
;                         dst[0] = pk2(y0, y1); dst[1] = pk2(y2, y3); dst[2] = pk2(y4, y5); dst[3] = pk2(y6, y7); }
;                     v2u uu[8][2]; float bqv[8];
;                     { const float* bsg_ = A_->gm_bs + (size_t)jl * 1024 + g * 128;
; #pragma unroll
;                       for (int qb = 0; qb < 8; ++qb) bqv[qb] = bsg_[qb * 16 + fr]; }
	v_sub_f32_e32 v1, v1, v2
	v_mul_f32_e32 v1, v3, v1
	v_sub_f32_e32 v16, v16, v2
	v_fma_f32 v1, v24, v1, v32
	v_mul_f32_e32 v16, v3, v16
	v_sub_f32_e32 v36, v36, v2
	v_sub_f32_e32 v17, v17, v2
	v_lshlrev_b32_e32 v37, 16, v18
	v_and_b32_e32 v18, 0xffff0000, v18
	v_fma_f32 v16, v25, v16, v33
	v_mul_f32_e32 v36, v3, v36
	v_mul_f32_e32 v17, v3, v17
	v_sub_f32_e32 v37, v37, v2
	v_sub_f32_e32 v18, v18, v2
	v_lshlrev_b32_e32 v38, 16, v19
	v_and_b32_e32 v19, 0xffff0000, v19
	v_cvt_pk_bf16_f32 v1, v1, v16
	v_fma_f32 v36, v26, v36, v34
	v_fma_f32 v17, v27, v17, v35
	v_mul_f32_e32 v37, v3, v37
	v_mul_f32_e32 v18, v3, v18
	v_sub_f32_e32 v38, v38, v2
	v_sub_f32_e32 v2, v19, v2
	ds_write_b32 v244, v1 offset:1024
	v_cvt_pk_bf16_f32 v1, v36, v17
	v_fma_f32 v37, v20, v37, v28
	v_fma_f32 v18, v21, v18, v29
	v_mul_f32_e32 v38, v3, v38
	v_mul_f32_e32 v2, v3, v2
	ds_write_b32 v244, v1 offset:1028
	v_cvt_pk_bf16_f32 v1, v37, v18
	v_fma_f32 v38, v22, v38, v30
	v_fma_f32 v2, v23, v2, v31
	ds_write_b32 v244, v1 offset:1032
	v_cvt_pk_bf16_f32 v1, v38, v2
	ds_write_b32 v244, v1 offset:1036
	v_lshl_add_u32 v1, v201, 3, 0
	ds_read_b64 v[2:3], v1
	v_lshlrev_b32_e32 v1, 16, v12
	v_and_b32_e32 v12, 0xffff0000, v12
	v_lshlrev_b32_e32 v16, 16, v13
	v_and_b32_e32 v13, 0xffff0000, v13
	s_waitcnt lgkmcnt(0)
	v_sub_f32_e32 v1, v1, v2
	v_mul_f32_e32 v1, v3, v1
	v_sub_f32_e32 v12, v12, v2
	v_fma_f32 v1, v24, v1, v32
	v_mul_f32_e32 v12, v3, v12
	v_sub_f32_e32 v16, v16, v2
	v_sub_f32_e32 v13, v13, v2
	v_lshlrev_b32_e32 v17, 16, v14
	v_and_b32_e32 v14, 0xffff0000, v14
	v_fma_f32 v12, v25, v12, v33
	v_mul_f32_e32 v16, v3, v16
	v_mul_f32_e32 v13, v3, v13
	v_sub_f32_e32 v17, v17, v2
	v_sub_f32_e32 v14, v14, v2
	v_lshlrev_b32_e32 v18, 16, v15
	v_and_b32_e32 v15, 0xffff0000, v15
	v_cvt_pk_bf16_f32 v1, v1, v12
	v_fma_f32 v16, v26, v16, v34
	v_fma_f32 v13, v27, v13, v35
	v_mul_f32_e32 v17, v3, v17
	v_mul_f32_e32 v14, v3, v14
	v_sub_f32_e32 v18, v18, v2
	v_sub_f32_e32 v2, v15, v2
	ds_write_b32 v245, v1 offset:1024
	v_cvt_pk_bf16_f32 v1, v16, v13
	v_fma_f32 v17, v20, v17, v28
	v_fma_f32 v14, v21, v14, v29
	v_mul_f32_e32 v18, v3, v18
	v_mul_f32_e32 v2, v3, v2
	ds_write_b32 v245, v1 offset:1028
	v_cvt_pk_bf16_f32 v1, v17, v14
	v_fma_f32 v18, v22, v18, v30
	v_fma_f32 v2, v23, v2, v31
	ds_write_b32 v245, v1 offset:1032
	v_cvt_pk_bf16_f32 v1, v18, v2
	ds_write_b32 v245, v1 offset:1036
	v_lshl_add_u32 v1, v211, 3, 0
	ds_read_b64 v[2:3], v1
	v_lshlrev_b32_e32 v1, 16, v8
	v_and_b32_e32 v8, 0xffff0000, v8
	v_lshlrev_b32_e32 v12, 16, v9
	v_and_b32_e32 v9, 0xffff0000, v9
	s_waitcnt lgkmcnt(0)
	v_sub_f32_e32 v1, v1, v2
	v_mul_f32_e32 v1, v3, v1
	v_sub_f32_e32 v8, v8, v2
	v_fma_f32 v1, v24, v1, v32
	v_mul_f32_e32 v8, v3, v8
	v_sub_f32_e32 v12, v12, v2
	v_sub_f32_e32 v9, v9, v2
	v_lshlrev_b32_e32 v13, 16, v10
	v_and_b32_e32 v10, 0xffff0000, v10
	v_fma_f32 v8, v25, v8, v33
	v_mul_f32_e32 v12, v3, v12
	v_mul_f32_e32 v9, v3, v9
	v_sub_f32_e32 v13, v13, v2
	v_sub_f32_e32 v10, v10, v2
	v_lshlrev_b32_e32 v14, 16, v11
	v_and_b32_e32 v11, 0xffff0000, v11
	v_cvt_pk_bf16_f32 v1, v1, v8
	v_fma_f32 v12, v26, v12, v34
	v_fma_f32 v9, v27, v9, v35
	v_mul_f32_e32 v13, v3, v13
	v_mul_f32_e32 v10, v3, v10
	v_sub_f32_e32 v14, v14, v2
	v_sub_f32_e32 v2, v11, v2
	ds_write_b32 v248, v1 offset:1024
	v_cvt_pk_bf16_f32 v1, v12, v9
	v_fma_f32 v13, v20, v13, v28
	v_fma_f32 v10, v21, v10, v29
	v_mul_f32_e32 v14, v3, v14
	v_mul_f32_e32 v2, v3, v2
	ds_write_b32 v248, v1 offset:1028
	v_cvt_pk_bf16_f32 v1, v13, v10
	v_fma_f32 v14, v22, v14, v30
	v_fma_f32 v2, v23, v2, v31
	ds_write_b32 v248, v1 offset:1032
	v_cvt_pk_bf16_f32 v1, v14, v2
	ds_write_b32 v248, v1 offset:1036
	v_lshl_add_u32 v1, v230, 3, 0
	ds_read_b64 v[2:3], v1
	v_lshlrev_b32_e32 v1, 16, v4
	v_and_b32_e32 v4, 0xffff0000, v4
	v_lshlrev_b32_e32 v8, 16, v5
	v_and_b32_e32 v5, 0xffff0000, v5
	s_waitcnt lgkmcnt(0)
	v_sub_f32_e32 v1, v1, v2
	v_mul_f32_e32 v1, v3, v1
	v_sub_f32_e32 v4, v4, v2
	v_fma_f32 v1, v24, v1, v32
	v_mul_f32_e32 v4, v3, v4
	v_sub_f32_e32 v8, v8, v2
	v_sub_f32_e32 v5, v5, v2
	v_lshlrev_b32_e32 v9, 16, v6
	v_and_b32_e32 v6, 0xffff0000, v6
	v_fma_f32 v4, v25, v4, v33
	v_mul_f32_e32 v8, v3, v8
	v_mul_f32_e32 v5, v3, v5
	v_sub_f32_e32 v9, v9, v2
	v_sub_f32_e32 v6, v6, v2
	v_lshlrev_b32_e32 v10, 16, v7
	v_and_b32_e32 v7, 0xffff0000, v7
	v_cvt_pk_bf16_f32 v1, v1, v4
	v_fma_f32 v8, v26, v8, v34
	v_fma_f32 v5, v27, v5, v35
	v_mul_f32_e32 v9, v3, v9
	v_mul_f32_e32 v6, v3, v6
	v_sub_f32_e32 v10, v10, v2
	v_sub_f32_e32 v2, v7, v2
	ds_write_b32 v249, v1 offset:1024
	v_cvt_pk_bf16_f32 v1, v8, v5
	v_fma_f32 v9, v20, v9, v28
	v_fma_f32 v6, v21, v6, v29
	v_mul_f32_e32 v10, v3, v10
	v_mul_f32_e32 v2, v3, v2
	ds_write_b32 v249, v1 offset:1028
	v_cvt_pk_bf16_f32 v1, v9, v6
	v_fma_f32 v10, v22, v10, v30
	v_fma_f32 v2, v23, v2, v31
	ds_write_b32 v249, v1 offset:1032
	v_cvt_pk_bf16_f32 v1, v10, v2
	s_load_dwordx2 s[14:15], s[0:1], 0x98
	ds_write_b32 v249, v1 offset:1036
	v_or_b32_e32 v1, 16, v140
	v_mov_b32_e32 v3, v234
	v_mov_b32_e32 v68, v0
	s_waitcnt lgkmcnt(0)
; __global__ void __launch_bounds__(NWAVES * 64, 2) fwd_kernel(Args args) {
;     ...
;                     v2u uu[8][2]; float bqv[8];
;                     { const float* bsg_ = A_->gm_bs + (size_t)jl * 1024 + g * 128;
; #pragma unroll
;                       for (int qb = 0; qb < 8; ++qb) bqv[qb] = bsg_[qb * 16 + fr]; }
; #pragma unroll
;                     for (int qb = 0; qb < 8; ++qb)
; #pragma unroll
;                         for (int cb = 0; cb < 2; ++cb) uu[qb][cb] = *(const v2u*)(FB + (size_t)(row0 + qb * 16 + fr) * 4096 + c0 + wave * 32 + cb * 16 + fq * 4);
;                     __syncthreads();
;                     { const int itn_ = it + G < 1024 ? it + G : it; SP_PREFETCH(itn_); }
	s_add_u32 s8, s14, s6
	s_addc_u32 s15, s15, s7
	s_lshl_b32 s14, s18, 9
	s_add_u32 s14, s8, s14
	s_addc_u32 s15, s15, 0
	s_lshl_b32 s8, s17, 1
	v_lshl_add_u64 v[4:5], v[150:151], 0, s[8:9]
	s_lshl_b32 s8, s19, 4
	s_and_b32 s8, s8, 0xffffff80
	v_or_b32_e32 v226, s8, v140
	v_or_b32_e32 v222, s8, v1
	v_or_b32_e32 v1, 32, v140
	v_ashrrev_i32_e32 v227, 31, v226
	v_ashrrev_i32_e32 v223, 31, v222
	v_or_b32_e32 v204, s8, v1
	v_or_b32_e32 v1, 48, v140
	v_lshlrev_b64 v[6:7], 13, v[226:227]
	v_lshlrev_b64 v[8:9], 13, v[222:223]
	v_or_b32_e32 v198, s8, v1
	v_or_b32_e32 v1, 64, v140
	v_lshl_add_u64 v[6:7], v[4:5], 0, v[6:7]
	v_lshl_add_u64 v[8:9], v[4:5], 0, v[8:9]
	v_ashrrev_i32_e32 v205, 31, v204
	v_ashrrev_i32_e32 v199, 31, v198
	v_or_b32_e32 v190, s8, v1
	v_or_b32_e32 v1, 0x50, v140
	global_load_dword v210, v250, s[14:15]
	global_load_dword v200, v250, s[14:15] offset:64
	global_load_dword v188, v250, s[14:15] offset:128
	global_load_dword v180, v250, s[14:15] offset:192
	global_load_dword v170, v250, s[14:15] offset:256
	global_load_dword v162, v250, s[14:15] offset:320
	global_load_dword v160, v250, s[14:15] offset:384
	global_load_dword v2, v250, s[14:15] offset:448
	global_load_dwordx2 v[228:229], v[6:7], off
	global_load_dwordx2 v[224:225], v[6:7], off offset:32
	global_load_dwordx2 v[220:221], v[8:9], off
	global_load_dwordx2 v[208:209], v[8:9], off offset:32
	v_lshlrev_b64 v[6:7], 13, v[204:205]
	v_lshlrev_b64 v[8:9], 13, v[198:199]
	v_or_b32_e32 v184, s8, v1
	v_or_b32_e32 v1, 0x60, v140
	s_add_i32 s100, s100, 1
	s_bitcmp1_b32 s100, 0
	s_cselect_b32 s101, 8, -7
	s_add_i32 s18, s19, s101
	v_lshl_add_u64 v[6:7], v[4:5], 0, v[6:7]
	v_lshl_add_u64 v[8:9], v[4:5], 0, v[8:9]
	v_ashrrev_i32_e32 v191, 31, v190
	v_ashrrev_i32_e32 v185, 31, v184
	v_or_b32_e32 v174, s8, v1
	v_or_b32_e32 v1, 0x70, v140
	s_cmp_gt_i32 s100, 3
	global_load_dwordx2 v[206:207], v[6:7], off
	global_load_dwordx2 v[202:203], v[6:7], off offset:32
	global_load_dwordx2 v[196:197], v[8:9], off
	global_load_dwordx2 v[194:195], v[8:9], off offset:32
	v_lshlrev_b64 v[6:7], 13, v[190:191]
	v_lshlrev_b64 v[8:9], 13, v[184:185]
	v_or_b32_e32 v168, s8, v1
	s_cselect_b64 s[14:15], -1, 0
	s_cmp_lt_i32 s100, 4
	v_lshl_add_u64 v[6:7], v[4:5], 0, v[6:7]
	v_lshl_add_u64 v[8:9], v[4:5], 0, v[8:9]
	v_ashrrev_i32_e32 v175, 31, v174
	v_ashrrev_i32_e32 v169, 31, v168
	s_cselect_b32 s8, s18, s19
	global_load_dwordx2 v[192:193], v[6:7], off
	global_load_dwordx2 v[186:187], v[6:7], off offset:32
	global_load_dwordx2 v[182:183], v[8:9], off
	global_load_dwordx2 v[178:179], v[8:9], off offset:32
	v_lshlrev_b64 v[6:7], 13, v[174:175]
	v_lshlrev_b64 v[8:9], 13, v[168:169]
	s_lshl_b32 s16, s8, 4
	v_lshl_add_u64 v[6:7], v[4:5], 0, v[6:7]
	v_lshl_add_u64 v[4:5], v[4:5], 0, v[8:9]
	s_and_b32 s16, s16, 0xffffff80
	global_load_dwordx2 v[176:177], v[6:7], off
	global_load_dwordx2 v[172:173], v[6:7], off offset:32
	global_load_dwordx2 v[166:167], v[4:5], off
	global_load_dwordx2 v[164:165], v[4:5], off offset:32
	v_add_u32_e32 v4, s16, v161
	v_ashrrev_i32_e32 v5, 31, v4
	v_lshlrev_b64 v[4:5], 13, v[4:5]
	s_lshl_b32 s8, s8, 9
	v_add_u32_e32 v6, s16, v163
	v_lshl_add_u64 v[4:5], s[2:3], 0, v[4:5]
	s_and_b32 s8, s8, 0xe00
	v_ashrrev_i32_e32 v7, 31, v6
	v_lshl_add_u64 v[4:5], v[4:5], 0, s[8:9]
	v_lshlrev_b64 v[6:7], 13, v[6:7]
	v_lshl_add_u64 v[4:5], v[4:5], 0, v[212:213]
	s_mov_b32 s19, 0x7801000
	v_lshl_add_u64 v[6:7], s[2:3], 0, v[6:7]
	v_add_co_u32_e32 v4, vcc, s19, v4
	v_lshl_add_u64 v[6:7], v[6:7], 0, s[8:9]
	s_nop 0
	v_addc_co_u32_e32 v5, vcc, 0, v5, vcc
	v_lshl_add_u64 v[6:7], v[6:7], 0, v[212:213]
	v_add_co_u32_e32 v6, vcc, s19, v6
	s_barrier
; __global__ void __launch_bounds__(NWAVES * 64, 2) fwd_kernel(Args args) {
;     ...
;                     { const int itn_ = it + G < 1024 ? it + G : it; SP_PREFETCH(itn_); }
;                     f32x4 acc[2][8];
; #pragma unroll
;                     for (int cb = 0; cb < 2; ++cb)
; #pragma unroll
;                         for (int qb = 0; qb < 8; ++qb) acc[cb][qb] = zero4;
	s_nop 0
	v_addc_co_u32_e32 v7, vcc, 0, v7, vcc
	global_load_dwordx4 v[48:51], v[4:5], off
	global_load_dwordx4 v[44:47], v[6:7], off
	v_add_u32_e32 v4, s16, v171
	v_ashrrev_i32_e32 v5, 31, v4
	v_lshlrev_b64 v[4:5], 13, v[4:5]
	v_add_u32_e32 v6, s16, v181
	v_lshl_add_u64 v[4:5], s[2:3], 0, v[4:5]
	v_ashrrev_i32_e32 v7, 31, v6
	v_lshl_add_u64 v[4:5], v[4:5], 0, s[8:9]
	v_lshlrev_b64 v[6:7], 13, v[6:7]
	v_lshl_add_u64 v[4:5], v[4:5], 0, v[212:213]
	v_lshl_add_u64 v[6:7], s[2:3], 0, v[6:7]
	v_add_co_u32_e32 v4, vcc, s19, v4
	v_lshl_add_u64 v[6:7], v[6:7], 0, s[8:9]
	s_nop 0
	v_addc_co_u32_e32 v5, vcc, 0, v5, vcc
	v_lshl_add_u64 v[6:7], v[6:7], 0, v[212:213]
	v_add_co_u32_e32 v6, vcc, s19, v6
	v_add_u32_e32 v52, s16, v141
	s_nop 0
	v_addc_co_u32_e32 v7, vcc, 0, v7, vcc
	global_load_dwordx4 v[40:43], v[4:5], off
	global_load_dwordx4 v[36:39], v[6:7], off
	v_add_u32_e32 v4, s16, v189
	v_ashrrev_i32_e32 v5, 31, v4
	v_lshlrev_b64 v[4:5], 13, v[4:5]
	v_add_u32_e32 v6, s16, v201
	v_lshl_add_u64 v[4:5], s[2:3], 0, v[4:5]
	v_ashrrev_i32_e32 v7, 31, v6
	v_lshl_add_u64 v[4:5], v[4:5], 0, s[8:9]
	v_lshlrev_b64 v[6:7], 13, v[6:7]
	v_lshl_add_u64 v[4:5], v[4:5], 0, v[212:213]
	v_lshl_add_u64 v[6:7], s[2:3], 0, v[6:7]
	v_add_co_u32_e32 v4, vcc, s19, v4
	v_lshl_add_u64 v[6:7], v[6:7], 0, s[8:9]
	s_nop 0
	v_addc_co_u32_e32 v5, vcc, 0, v5, vcc
	v_lshl_add_u64 v[6:7], v[6:7], 0, v[212:213]
	v_add_co_u32_e32 v6, vcc, s19, v6
	v_ashrrev_i32_e32 v53, 31, v52
	s_nop 0
	v_addc_co_u32_e32 v7, vcc, 0, v7, vcc
	global_load_dwordx4 v[16:19], v[4:5], off
	global_load_dwordx4 v[12:15], v[6:7], off
	v_add_u32_e32 v4, s16, v211
	v_ashrrev_i32_e32 v5, 31, v4
	v_lshlrev_b64 v[4:5], 13, v[4:5]
	v_add_u32_e32 v6, s16, v230
	v_lshl_add_u64 v[4:5], s[2:3], 0, v[4:5]
	v_ashrrev_i32_e32 v7, 31, v6
	v_lshl_add_u64 v[4:5], v[4:5], 0, s[8:9]
	v_lshlrev_b64 v[6:7], 13, v[6:7]
	v_lshl_add_u64 v[4:5], v[4:5], 0, v[212:213]
	v_lshl_add_u64 v[6:7], s[2:3], 0, v[6:7]
	v_add_co_u32_e32 v4, vcc, s19, v4
	v_lshl_add_u64 v[6:7], v[6:7], 0, s[8:9]
	s_nop 0
	v_addc_co_u32_e32 v5, vcc, 0, v5, vcc
	v_lshl_add_u64 v[6:7], v[6:7], 0, v[212:213]
	v_add_co_u32_e32 v6, vcc, 0x7801000, v6
	v_lshlrev_b64 v[52:53], 8, v[52:53]
	s_nop 0
	v_addc_co_u32_e32 v7, vcc, 0, v7, vcc
	v_lshl_add_u64 v[64:65], v[142:143], 0, v[52:53]
	global_load_dwordx4 v[8:11], v[4:5], off
	s_nop 0
	global_load_dwordx4 v[4:7], v[6:7], off
	s_nop 0
	global_load_dwordx4 v[52:55], v[64:65], off offset:48
	global_load_dwordx4 v[56:59], v[64:65], off offset:32
	global_load_dwordx4 v[60:63], v[64:65], off offset:16
	s_nop 0
	global_load_dwordx4 v[64:67], v[64:65], off
	s_mov_b32 s8, 4
	v_mov_b32_e32 v1, v235
	v_mov_b32_e32 v69, v0
	v_mov_b32_e32 v70, v0
	v_mov_b32_e32 v71, v0
	v_mov_b32_e32 v72, v0
	v_mov_b32_e32 v73, v0
	v_mov_b32_e32 v74, v0
	v_mov_b32_e32 v75, v0
	v_mov_b32_e32 v80, v0
	v_mov_b32_e32 v81, v0
	v_mov_b32_e32 v82, v0
	v_mov_b32_e32 v83, v0
	v_mov_b32_e32 v88, v0
	v_mov_b32_e32 v89, v0
	v_mov_b32_e32 v90, v0
	v_mov_b32_e32 v91, v0
	v_mov_b32_e32 v96, v0
	v_mov_b32_e32 v97, v0
	v_mov_b32_e32 v98, v0
	v_mov_b32_e32 v99, v0
	v_mov_b32_e32 v104, v0
	v_mov_b32_e32 v105, v0
	v_mov_b32_e32 v106, v0
	v_mov_b32_e32 v107, v0
	v_mov_b32_e32 v112, v0
	v_mov_b32_e32 v113, v0
	v_mov_b32_e32 v114, v0
	v_mov_b32_e32 v115, v0
	v_mov_b32_e32 v120, v0
	v_mov_b32_e32 v121, v0
	v_mov_b32_e32 v122, v0
	v_mov_b32_e32 v123, v0
	v_mov_b32_e32 v76, v0
	v_mov_b32_e32 v77, v0
	v_mov_b32_e32 v78, v0
	v_mov_b32_e32 v79, v0
	v_mov_b32_e32 v84, v0
	v_mov_b32_e32 v85, v0
	v_mov_b32_e32 v86, v0
	v_mov_b32_e32 v87, v0
	v_mov_b32_e32 v92, v0
	v_mov_b32_e32 v93, v0
	v_mov_b32_e32 v94, v0
	v_mov_b32_e32 v95, v0
	v_mov_b32_e32 v100, v0
	v_mov_b32_e32 v101, v0
	v_mov_b32_e32 v102, v0
	v_mov_b32_e32 v103, v0
	v_mov_b32_e32 v108, v0
	v_mov_b32_e32 v109, v0
	v_mov_b32_e32 v110, v0
	v_mov_b32_e32 v111, v0
	v_mov_b32_e32 v116, v0
	v_mov_b32_e32 v117, v0
	v_mov_b32_e32 v118, v0
	v_mov_b32_e32 v119, v0
	v_mov_b32_e32 v124, v0
	v_mov_b32_e32 v125, v0
	v_mov_b32_e32 v126, v0
	v_mov_b32_e32 v127, v0
	v_mov_b32_e32 v128, v0
	v_mov_b32_e32 v129, v0
	v_mov_b32_e32 v130, v0
	v_mov_b32_e32 v131, v0

; __device__ __forceinline__ unsigned xb_add(unsigned* p, unsigned v) { return __hip_atomic_fetch_add(p, v, __ATOMIC_RELAXED, __HIP_MEMORY_SCOPE_AGENT); }
; __device__ __forceinline__ void xcd_barrier(const XcdBarrier& b, int tid) {
;     asm volatile("s_waitcnt vmcnt(0)" ::: "memory");
;     __syncthreads();
;     if (tid == 0) {
;         unsigned* bar = b.bar;
;         __builtin_amdgcn_s_waitcnt(0);
;         unsigned nloc = b.st[0], nx = b.st[1];
;         if (nloc == 0u) { xcd_barrier_complete(bar, b.x, nloc, nx); b.st[0] = nloc; b.st[1] = nx; }
;         const unsigned old = xb_add(&bar[XB_XSUB(b.x)], 1u);
;         const unsigned gen = old / nloc;
;         if (old + 1u == (gen + 1u) * nloc) {
;             __builtin_amdgcn_fence(__ATOMIC_RELEASE, "agent");
;             asm volatile("s_waitcnt vmcnt(0)" ::: "memory");
;             const unsigned og = xb_add(&bar[XB_TOP], 1u);
;             const unsigned tg = og / nx;
;             if (og + 1u == (tg + 1u) * nx) xb_add(&bar[XB_TOPGEN], 1u);
.LBB0_376:
	v_readlane_b32 s0, v254, 2
	s_add_i32 s4, s0, 2
	s_cmp_lt_i32 s4, s81
	s_cbranch_scc0 .LBB0_442
	v_readlane_b32 s100, v255, 57
	s_cmp_lg_u32 s100, 0
	s_cbranch_scc0 .Lgq_orig_gate
	s_waitcnt vmcnt(0) lgkmcnt(0)
	s_barrier
	v_readlane_b32 s100, v255, 59
	s_add_i32 s100, s100, 1
	v_writelane_b32 v255, s100, 59
	v_cmp_eq_u32_e32 vcc, 0, v215
	s_and_saveexec_b64 s[0:1], vcc
	s_cbranch_execz .Lgq_w_gate
	s_load_dwordx2 s[2:3], s[94:95], 0xb8
	v_readlane_b32 s101, v255, 12
	s_and_b32 s101, s101, 63
	s_lshl_b32 s101, s101, 6
	s_cmp_lt_u32 s101, 0x800
	s_movk_i32 s7, 0x1400
	s_cselect_b32 s7, 0xc00, s7
	s_add_i32 s101, s101, s7
	s_lshl_b32 s100, s100, 2
	v_mov_b32_e32 v0, s101
	v_mov_b32_e32 v1, 1
	s_waitcnt lgkmcnt(0)
	s_add_u32 s2, s2, 0xe0000
	s_addc_u32 s3, s3, 0
	global_atomic_add v0, v1, s[2:3]
	buffer_inv sc1
	s_mov_b32 s6, 0
